# moba_list: one vector atomic per wave instead of up to 15 serialized returning atomics
# speedup vs baseline: 1.0232x; 1.0213x over previous
; __device__ __forceinline__ int opq(int v) { asm volatile("" : "+v"(v)); return v; }
; __device__ __forceinline__ int lane_id() { return (int)__builtin_amdgcn_mbcnt_hi(~0u, __builtin_amdgcn_mbcnt_lo(~0u, 0u)); }
; __device__ __forceinline__ void moba_list_item(const Ptrs& P, int bh, int j) {
;     const int tid = opq((P.wave << 6) | lane_id()), lane = tid & 63, wid = __builtin_amdgcn_readfirstlane(tid >> 6), r32 = lane & 31, hi = lane >> 5;
;     const int b = bh >> 3, h = bh & 7, t = j * 256 + 32 * wid + r32;
;     bf16x8 qr[8]; moba_load_q(qr, P, (size_t)(b * SEQ + t), h, hi);
;     f32x16 ga = {};
; #pragma unroll
;     for (int ks = 0; ks < 8; ++ks) { const bf16x8 kf = *(const bf16x8*)(P.KM() + ((size_t)(bh * 16 + (r32 & 15))) * 128 + ks * 16 + hi * 8);
;         ga = __builtin_amdgcn_mfma_f32_32x32x16_bf16(kf, qr[ks], ga, 0, 0, 0); }
;     float g[16];
; #pragma unroll
;     for (int e = 0; e < 8; ++e) { const float mine = ga[e], oth = __shfl_xor(mine, 32);
;         const float lo = hi ? oth : mine, hh = hi ? mine : oth;
;         g[(e & 3) + 8 * (e >> 2)] = lo; g[4 + (e & 3) + 8 * (e >> 2)] = hh; }
;     const float NI = -3.0e38f;
;     unsigned sel = 0u;
; #pragma unroll
;     for (int pass = 0; pass < 3; ++pass) { float best = NI; int bi = -1;
; #pragma unroll
;         for (int n = 0; n < 16; ++n) { const bool ok = (n < j) && (((sel >> n) & 1u) == 0u) && (g[n] > best); best = ok ? g[n] : best; bi = ok ? n : bi; }
.LBB0_758:
	s_and_b32 s0, s75, 15
	s_cmp_eq_u32 s0, 0
	s_cbranch_scc1 .LBB0_757
	s_and_b32 s2, s75, -16
	s_ashr_i32 s3, s2, 31
	s_lshl_b64 s[4:5], s[2:3], 2
	s_add_u32 s26, s40, s4
	s_addc_u32 s27, s41, s5
	s_lshl_b64 s[2:3], s[2:3], 14
	v_mov_b32_e32 v23, v19
	s_add_u32 s28, s42, s2
	s_addc_u32 s29, s43, s3
	v_readfirstlane_b32 s2, v23
	s_ashr_i32 s2, s2, 1
	s_lshl_b32 s3, s0, 8
	s_andn2_b32 s2, s2, 31
	s_ashr_i32 s1, s75, 4
	s_add_i32 s2, s2, s3
	v_and_or_b32 v21, v23, 31, s2
	s_lshl_b32 s2, s1, 9
	s_and_b32 s2, s2, 0xfffff000
	v_add_u32_e32 v6, s2, v21
	s_lshl_b32 s1, s1, 8
	v_mov_b64_e32 v[4:5], s[14:15]
	s_and_b32 s20, s1, 0x700
	v_lshrrev_b32_e32 v2, 1, v23
	v_mad_i64_i32 v[4:5], s[2:3], v6, s64, v[4:5]
	v_mov_b64_e32 v[0:1], s[22:23]
	v_and_b32_e32 v16, 16, v2
	v_lshl_add_u64 v[4:5], v[4:5], 0, s[20:21]
	v_mad_i64_i32 v[0:1], s[2:3], v6, s64, v[0:1]
	v_lshl_add_u64 v[4:5], v[4:5], 0, v[16:17]
	v_lshl_add_u64 v[0:1], v[0:1], 0, s[20:21]
	v_add_co_u32_e32 v4, vcc, s65, v4
	v_lshl_add_u64 v[0:1], v[0:1], 0, v[16:17]
	s_nop 0
	v_addc_co_u32_e32 v5, vcc, 0, v5, vcc
	global_load_dwordx4 v[0:3], v[0:1], off
	s_nop 0
	global_load_dwordx4 v[24:27], v[4:5], off offset:32
	global_load_dwordx4 v[28:31], v[4:5], off offset:64
	global_load_dwordx4 v[32:35], v[4:5], off offset:96
	global_load_dwordx4 v[36:39], v[4:5], off offset:128
	global_load_dwordx4 v[40:43], v[4:5], off offset:160
	global_load_dwordx4 v[44:47], v[4:5], off offset:192
	global_load_dwordx4 v[48:51], v[4:5], off offset:224
	v_bfi_b32 v4, 15, v23, s75
	v_ashrrev_i32_e32 v5, 31, v4
	v_lshlrev_b64 v[4:5], 8, v[4:5]
	v_lshl_add_u64 v[4:5], s[24:25], 0, v[4:5]
	v_lshl_add_u64 v[56:57], v[4:5], 0, v[16:17]
	global_load_dwordx4 v[4:7], v[56:57], off
	global_load_dwordx4 v[52:55], v[56:57], off offset:32
	s_and_b32 s76, s74, 15
	s_cmp_lg_u32 s0, 1
	s_cselect_b64 s[6:7], -1, 0
	s_mov_b32 s20, 0
	s_waitcnt vmcnt(1)
	v_mfma_f32_32x32x16_bf16 v[0:15], v[4:7], v[0:3], 0
	s_waitcnt vmcnt(0)
	v_mfma_f32_32x32x16_bf16 v[0:15], v[52:55], v[24:27], v[0:15]
	global_load_dwordx4 v[24:27], v[56:57], off offset:64
	s_waitcnt vmcnt(0)
	v_mfma_f32_32x32x16_bf16 v[0:15], v[24:27], v[28:31], v[0:15]
	global_load_dwordx4 v[24:27], v[56:57], off offset:96
	s_waitcnt vmcnt(0)
	v_mfma_f32_32x32x16_bf16 v[0:15], v[24:27], v[32:35], v[0:15]
	global_load_dwordx4 v[24:27], v[56:57], off offset:128
	s_waitcnt vmcnt(0)
	v_mfma_f32_32x32x16_bf16 v[0:15], v[24:27], v[36:39], v[0:15]
	global_load_dwordx4 v[24:27], v[56:57], off offset:160
	s_waitcnt vmcnt(0)
	v_mfma_f32_32x32x16_bf16 v[0:15], v[24:27], v[40:43], v[0:15]
	global_load_dwordx4 v[24:27], v[56:57], off offset:192
	s_waitcnt vmcnt(0)
	v_mfma_f32_32x32x16_bf16 v[0:15], v[24:27], v[44:47], v[0:15]
	global_load_dwordx4 v[24:27], v[56:57], off offset:224
	s_waitcnt vmcnt(0)
	v_mfma_f32_32x32x16_bf16 v[0:15], v[24:27], v[48:51], v[0:15]
	s_nop 11
	v_and_b32_e32 v8, 63, v23
	v_cmp_gt_u32_e64 s[2:3], 32, v8
	ds_bpermute_b32 v9, v18, v0
	s_waitcnt lgkmcnt(0)
	v_cndmask_b32_e64 v25, v9, v0, s[2:3]
	v_cndmask_b32_e64 v14, v0, v9, s[2:3]
	ds_bpermute_b32 v0, v18, v1
	v_cmp_nlt_f32_e32 vcc, s66, v25
	s_waitcnt lgkmcnt(0)
	v_cndmask_b32_e64 v24, v0, v1, s[2:3]
	v_cndmask_b32_e64 v13, v1, v0, s[2:3]
	ds_bpermute_b32 v0, v18, v2
	s_waitcnt lgkmcnt(0)
	v_cndmask_b32_e64 v16, v0, v2, s[2:3]
	v_cndmask_b32_e64 v12, v2, v0, s[2:3]
	ds_bpermute_b32 v0, v18, v3
	s_waitcnt lgkmcnt(0)
	v_cndmask_b32_e64 v15, v0, v3, s[2:3]
	v_cndmask_b32_e64 v11, v3, v0, s[2:3]
	ds_bpermute_b32 v0, v18, v4
	ds_bpermute_b32 v3, v18, v7
	s_waitcnt lgkmcnt(1)
	v_cndmask_b32_e64 v10, v0, v4, s[2:3]
	v_cndmask_b32_e64 v2, v4, v0, s[2:3]
	ds_bpermute_b32 v0, v18, v5
	s_waitcnt lgkmcnt(1)
	v_cndmask_b32_e64 v3, v3, v7, s[2:3]
	s_waitcnt lgkmcnt(0)
	v_cndmask_b32_e64 v9, v0, v5, s[2:3]
	v_cndmask_b32_e64 v1, v5, v0, s[2:3]
	ds_bpermute_b32 v0, v18, v6
	v_cndmask_b32_e64 v5, 0, -1, vcc
	s_waitcnt lgkmcnt(0)
	v_cndmask_b32_e64 v4, v0, v6, s[2:3]
	v_cndmask_b32_e64 v0, v6, v0, s[2:3]
	v_cndmask_b32_e32 v6, v25, v20, vcc
	v_cmp_gt_f32_e64 s[4:5], v24, v6
	s_and_b64 s[4:5], s[6:7], s[4:5]
	s_cmp_gt_u32 s0, 2
	v_cndmask_b32_e64 v6, v6, v24, s[4:5]
	v_cndmask_b32_e64 v5, v5, 1, s[4:5]
	s_cselect_b64 s[62:63], -1, 0
	v_cmp_gt_f32_e64 s[4:5], v16, v6
	s_and_b64 s[4:5], s[62:63], s[4:5]
	s_cmp_gt_u32 s0, 3
	v_cndmask_b32_e64 v6, v6, v16, s[4:5]
	v_cndmask_b32_e64 v5, v5, 2, s[4:5]
	s_cselect_b64 s[60:61], -1, 0
	v_cmp_gt_f32_e64 s[4:5], v15, v6
	s_and_b64 s[4:5], s[60:61], s[4:5]
	s_cmp_gt_u32 s0, 4
	v_cndmask_b32_e64 v6, v6, v15, s[4:5]
	v_cndmask_b32_e64 v5, v5, 3, s[4:5]
	s_cselect_b64 s[58:59], -1, 0
	v_cmp_gt_f32_e64 s[4:5], v14, v6
	s_and_b64 s[4:5], s[58:59], s[4:5]
	s_cmp_gt_u32 s0, 5
	v_cndmask_b32_e64 v6, v6, v14, s[4:5]
	v_cndmask_b32_e64 v5, v5, 4, s[4:5]
	s_cselect_b64 s[56:57], -1, 0
	v_cmp_gt_f32_e64 s[4:5], v13, v6
	s_and_b64 s[4:5], s[56:57], s[4:5]
	s_cmp_gt_u32 s0, 6
	v_cndmask_b32_e64 v6, v6, v13, s[4:5]
	v_cndmask_b32_e64 v5, v5, 5, s[4:5]
	s_cselect_b64 s[54:55], -1, 0
	v_cmp_gt_f32_e64 s[4:5], v12, v6
	s_and_b64 s[4:5], s[54:55], s[4:5]
	s_cmp_gt_u32 s0, 7
	v_cndmask_b32_e64 v6, v6, v12, s[4:5]
	v_cndmask_b32_e64 v5, v5, 6, s[4:5]
	s_cselect_b64 s[52:53], -1, 0
	v_cmp_gt_f32_e64 s[4:5], v11, v6
	s_and_b64 s[4:5], s[52:53], s[4:5]
	s_cmp_gt_u32 s0, 8
	v_cndmask_b32_e64 v6, v6, v11, s[4:5]
	v_cndmask_b32_e64 v5, v5, 7, s[4:5]
	s_cselect_b64 s[50:51], -1, 0
	v_cmp_gt_f32_e64 s[4:5], v10, v6
	s_and_b64 s[4:5], s[50:51], s[4:5]
	s_cmp_gt_u32 s0, 9
	v_cndmask_b32_e64 v6, v6, v10, s[4:5]
	v_cndmask_b32_e64 v5, v5, 8, s[4:5]
	s_cselect_b64 s[48:49], -1, 0
	v_cmp_gt_f32_e64 s[4:5], v9, v6
; __device__ __forceinline__ void moba_list_item(const Ptrs& P, int bh, int j) {
;     ...
;     for (int pass = 0; pass < 3; ++pass) { float best = NI; int bi = -1;
; #pragma unroll
;         for (int n = 0; n < 16; ++n) { const bool ok = (n < j) && (((sel >> n) & 1u) == 0u) && (g[n] > best); best = ok ? g[n] : best; bi = ok ? n : bi; }
;         if (bi >= 0) sel |= 1u << bi; }
	s_and_b64 s[4:5], s[48:49], s[4:5]
	s_cmp_gt_u32 s0, 10
	v_cndmask_b32_e64 v6, v6, v9, s[4:5]
	v_cndmask_b32_e64 v5, v5, 9, s[4:5]
	s_cselect_b64 s[46:47], -1, 0
	v_cmp_gt_f32_e64 s[4:5], v4, v6
	s_and_b64 s[4:5], s[46:47], s[4:5]
	s_cmp_gt_u32 s0, 11
	v_cndmask_b32_e64 v6, v6, v4, s[4:5]
	v_cndmask_b32_e64 v5, v5, 10, s[4:5]
	s_cselect_b64 s[44:45], -1, 0
	v_cmp_gt_f32_e64 s[4:5], v3, v6
	s_and_b64 s[4:5], s[44:45], s[4:5]
	s_cmp_gt_u32 s0, 12
	v_cndmask_b32_e64 v6, v6, v3, s[4:5]
	v_cndmask_b32_e64 v5, v5, 11, s[4:5]
	s_cselect_b64 s[36:37], -1, 0
	v_cmp_gt_f32_e64 s[4:5], v2, v6
	s_and_b64 s[4:5], s[36:37], s[4:5]
	s_cmp_gt_u32 s0, 13
	v_cndmask_b32_e64 v6, v6, v2, s[4:5]
	v_cndmask_b32_e64 v5, v5, 12, s[4:5]
	s_cselect_b64 s[34:35], -1, 0
	v_cmp_gt_f32_e64 s[4:5], v1, v6
	s_and_b64 s[4:5], s[34:35], s[4:5]
	s_cmp_eq_u32 s0, 15
	v_cndmask_b32_e64 v6, v6, v1, s[4:5]
	v_cndmask_b32_e64 v5, v5, 13, s[4:5]
	s_cselect_b64 s[30:31], -1, 0
	v_cmp_gt_f32_e64 s[4:5], v0, v6
	s_and_b64 s[0:1], s[30:31], s[4:5]
	v_cndmask_b32_e64 v5, v5, 14, s[0:1]
	v_lshlrev_b32_e64 v6, v5, 1
	v_cmp_lt_i32_e64 s[4:5], -1, v5
	s_nop 1
	v_cndmask_b32_e64 v5, 0, v6, s[4:5]
	v_and_b32_e32 v6, 1, v5
	v_cmp_eq_u32_e64 s[4:5], 1, v6
	s_or_b64 s[4:5], s[4:5], vcc
	v_and_b32_e32 v26, 2, v5
	v_cndmask_b32_e64 v6, 0, -1, s[4:5]
	v_cndmask_b32_e64 v7, v25, v20, s[4:5]
	v_cmp_eq_u32_e64 s[4:5], 0, v26
	s_and_b64 s[0:1], s[6:7], s[4:5]
	v_cmp_gt_f32_e64 s[4:5], v24, v7
	s_and_b64 s[4:5], s[0:1], s[4:5]
	v_and_b32_e32 v26, 4, v5
	v_cndmask_b32_e64 v6, v6, 1, s[4:5]
	v_cndmask_b32_e64 v7, v7, v24, s[4:5]
	v_cmp_eq_u32_e64 s[4:5], 0, v26
	s_and_b64 s[0:1], s[62:63], s[4:5]
	v_cmp_gt_f32_e64 s[4:5], v16, v7
	s_and_b64 s[4:5], s[0:1], s[4:5]
	v_and_b32_e32 v26, 8, v5
	v_cndmask_b32_e64 v6, v6, 2, s[4:5]
	v_cndmask_b32_e64 v7, v7, v16, s[4:5]
	v_cmp_eq_u32_e64 s[4:5], 0, v26
	s_and_b64 s[0:1], s[60:61], s[4:5]
	v_cmp_gt_f32_e64 s[4:5], v15, v7
	s_and_b64 s[4:5], s[0:1], s[4:5]
	v_and_b32_e32 v26, 16, v5
	v_cndmask_b32_e64 v6, v6, 3, s[4:5]
	v_cndmask_b32_e64 v7, v7, v15, s[4:5]
	v_cmp_eq_u32_e64 s[4:5], 0, v26
	s_and_b64 s[0:1], s[58:59], s[4:5]
	v_cmp_gt_f32_e64 s[4:5], v14, v7
	s_and_b64 s[4:5], s[0:1], s[4:5]
	v_and_b32_e32 v26, 32, v5
	v_cndmask_b32_e64 v6, v6, 4, s[4:5]
	v_cndmask_b32_e64 v7, v7, v14, s[4:5]
	v_cmp_eq_u32_e64 s[4:5], 0, v26
	s_and_b64 s[0:1], s[56:57], s[4:5]
	v_cmp_gt_f32_e64 s[4:5], v13, v7
	s_and_b64 s[4:5], s[0:1], s[4:5]
	v_and_b32_e32 v26, 64, v5
	v_cndmask_b32_e64 v6, v6, 5, s[4:5]
	v_cndmask_b32_e64 v7, v7, v13, s[4:5]
	v_cmp_eq_u32_e64 s[4:5], 0, v26
	s_and_b64 s[0:1], s[54:55], s[4:5]
	v_cmp_gt_f32_e64 s[4:5], v12, v7
	s_and_b64 s[4:5], s[0:1], s[4:5]
	v_and_b32_e32 v26, 0x80, v5
	v_cndmask_b32_e64 v6, v6, 6, s[4:5]
	v_cndmask_b32_e64 v7, v7, v12, s[4:5]
	v_cmp_eq_u32_e64 s[4:5], 0, v26
	s_and_b64 s[0:1], s[52:53], s[4:5]
	v_cmp_gt_f32_e64 s[4:5], v11, v7
	s_and_b64 s[4:5], s[0:1], s[4:5]
	v_and_b32_e32 v26, 0x100, v5
	v_cndmask_b32_e64 v6, v6, 7, s[4:5]
	v_cndmask_b32_e64 v7, v7, v11, s[4:5]
	v_cmp_eq_u32_e64 s[4:5], 0, v26
	s_and_b64 s[0:1], s[50:51], s[4:5]
	v_cmp_gt_f32_e64 s[4:5], v10, v7
	s_and_b64 s[4:5], s[0:1], s[4:5]
	v_and_b32_e32 v26, 0x200, v5
	v_cndmask_b32_e64 v6, v6, 8, s[4:5]
	v_cndmask_b32_e64 v7, v7, v10, s[4:5]
	v_cmp_eq_u32_e64 s[4:5], 0, v26
	s_and_b64 s[0:1], s[48:49], s[4:5]
	v_cmp_gt_f32_e64 s[4:5], v9, v7
	s_and_b64 s[4:5], s[0:1], s[4:5]
	v_and_b32_e32 v26, 0x400, v5
	v_cndmask_b32_e64 v6, v6, 9, s[4:5]
	v_cndmask_b32_e64 v7, v7, v9, s[4:5]
	v_cmp_eq_u32_e64 s[4:5], 0, v26
	s_and_b64 s[0:1], s[46:47], s[4:5]
	v_cmp_gt_f32_e64 s[4:5], v4, v7
	s_and_b64 s[4:5], s[0:1], s[4:5]
	v_and_b32_e32 v26, 0x800, v5
	v_cndmask_b32_e64 v6, v6, 10, s[4:5]
	v_cndmask_b32_e64 v7, v7, v4, s[4:5]
	v_cmp_eq_u32_e64 s[4:5], 0, v26
	s_and_b64 s[0:1], s[44:45], s[4:5]
	v_cmp_gt_f32_e64 s[4:5], v3, v7
	s_and_b64 s[4:5], s[0:1], s[4:5]
	v_and_b32_e32 v26, 0x1000, v5
	v_cndmask_b32_e64 v6, v6, 11, s[4:5]
	v_cndmask_b32_e64 v7, v7, v3, s[4:5]
	v_cmp_eq_u32_e64 s[4:5], 0, v26
	s_and_b64 s[0:1], s[36:37], s[4:5]
	v_cmp_gt_f32_e64 s[4:5], v2, v7
	s_and_b64 s[4:5], s[0:1], s[4:5]
	v_and_b32_e32 v26, 0x2000, v5
	v_cndmask_b32_e64 v6, v6, 12, s[4:5]
	v_cndmask_b32_e64 v7, v7, v2, s[4:5]
	v_cmp_eq_u32_e64 s[4:5], 0, v26
	s_and_b64 s[0:1], s[34:35], s[4:5]
	v_cmp_gt_f32_e64 s[4:5], v1, v7
	s_and_b64 s[4:5], s[0:1], s[4:5]
	v_and_b32_e32 v26, 0x4000, v5
	v_cndmask_b32_e64 v6, v6, 13, s[4:5]
	v_cndmask_b32_e64 v7, v7, v1, s[4:5]
	v_cmp_eq_u32_e64 s[4:5], 0, v26
	s_and_b64 s[0:1], s[30:31], s[4:5]
	v_cmp_gt_f32_e64 s[4:5], v0, v7
	s_and_b64 s[0:1], s[0:1], s[4:5]
	v_cndmask_b32_e64 v6, v6, 14, s[0:1]
	v_lshlrev_b32_e64 v7, v6, 1
	v_cmp_lt_i32_e64 s[4:5], -1, v6
	s_nop 1
	v_cndmask_b32_e64 v6, 0, v7, s[4:5]
	v_or_b32_e32 v7, v6, v5
	v_and_b32_e32 v26, 1, v7
	v_cmp_eq_u32_e64 s[4:5], 1, v26
	s_or_b64 vcc, s[4:5], vcc
	v_bitop3_b32 v27, v6, 2, v5 bitop3:0xc8
	v_cndmask_b32_e64 v26, 0, -1, vcc
	v_cndmask_b32_e32 v25, v25, v20, vcc
; __device__ __forceinline__ void moba_list_item(const Ptrs& P, int bh, int j) {
;     ...
;     for (int pass = 0; pass < 3; ++pass) { float best = NI; int bi = -1;
; #pragma unroll
;         for (int n = 0; n < 16; ++n) { const bool ok = (n < j) && (((sel >> n) & 1u) == 0u) && (g[n] > best); best = ok ? g[n] : best; bi = ok ? n : bi; }
;         if (bi >= 0) sel |= 1u << bi; }
;     for (int n = 0; n < j; ++n) {
;         const bool sb = (((sel >> n) & 1u) != 0u) && (hi == 0);
;         const unsigned long long mk = __ballot(sb);
;         if (mk != 0ull) {
;             unsigned base = 0u;
;             if (lane == 0) base = atomicAdd(P.SELCNT() + bh * 16 + n, (unsigned)__popcll(mk));
;             base = (unsigned)__builtin_amdgcn_readfirstlane((int)base);
;             if (sb) { const unsigned pos = base + (unsigned)__popcll(mk & ((1ull << lane) - 1ull)); const unsigned k = (unsigned)__popc(sel & ((1u << n) - 1u));
;                 if (pos < 4096u) P.LIST()[(size_t)(bh * 16 + n) * 4096 + pos] = (unsigned)t | (k << 12); }
	v_cmp_eq_u32_e32 vcc, 0, v27
	s_and_b64 s[0:1], s[6:7], vcc
	v_cmp_gt_f32_e32 vcc, v24, v25
	s_and_b64 vcc, s[0:1], vcc
	v_cmp_eq_u32_e64 s[4:5], 0, v8
	v_cndmask_b32_e32 v24, v25, v24, vcc
	v_bitop3_b32 v25, v6, 4, v5 bitop3:0xc8
	v_cndmask_b32_e64 v26, v26, 1, vcc
	v_cmp_eq_u32_e32 vcc, 0, v25
	s_and_b64 s[0:1], s[62:63], vcc
	v_cmp_gt_f32_e32 vcc, v16, v24
	s_and_b64 vcc, s[0:1], vcc
	s_nop 0
	v_cndmask_b32_e32 v16, v24, v16, vcc
	v_bitop3_b32 v24, v6, 8, v5 bitop3:0xc8
	v_cndmask_b32_e64 v25, v26, 2, vcc
	v_cmp_eq_u32_e32 vcc, 0, v24
	s_and_b64 s[0:1], s[60:61], vcc
	v_cmp_gt_f32_e32 vcc, v15, v16
	s_and_b64 vcc, s[0:1], vcc
	s_nop 0
	v_cndmask_b32_e32 v15, v16, v15, vcc
	v_bitop3_b32 v16, v6, 16, v5 bitop3:0xc8
	v_cndmask_b32_e64 v24, v25, 3, vcc
	v_cmp_eq_u32_e32 vcc, 0, v16
	s_and_b64 s[0:1], s[58:59], vcc
	v_cmp_gt_f32_e32 vcc, v14, v15
	s_and_b64 vcc, s[0:1], vcc
	s_nop 0
	v_cndmask_b32_e32 v14, v15, v14, vcc
	v_bitop3_b32 v15, v6, 32, v5 bitop3:0xc8
	v_cndmask_b32_e64 v16, v24, 4, vcc
	v_cmp_eq_u32_e32 vcc, 0, v15
	s_and_b64 s[0:1], s[56:57], vcc
	v_cmp_gt_f32_e32 vcc, v13, v14
	s_and_b64 vcc, s[0:1], vcc
	s_nop 0
	v_cndmask_b32_e32 v13, v14, v13, vcc
	v_bitop3_b32 v14, v6, 64, v5 bitop3:0xc8
	v_cndmask_b32_e64 v15, v16, 5, vcc
	v_cmp_eq_u32_e32 vcc, 0, v14
	s_and_b64 s[0:1], s[54:55], vcc
	v_cmp_gt_f32_e32 vcc, v12, v13
	s_and_b64 vcc, s[0:1], vcc
	s_nop 0
	v_cndmask_b32_e32 v12, v13, v12, vcc
	v_bitop3_b32 v13, v6, s67, v5 bitop3:0xc8
	v_cndmask_b32_e64 v14, v15, 6, vcc
	v_cmp_eq_u32_e32 vcc, 0, v13
	s_and_b64 s[0:1], s[52:53], vcc
	v_cmp_gt_f32_e32 vcc, v11, v12
	s_and_b64 vcc, s[0:1], vcc
	s_nop 0
	v_cndmask_b32_e32 v11, v12, v11, vcc
	v_bitop3_b32 v12, v6, s68, v5 bitop3:0xc8
	v_cndmask_b32_e64 v13, v14, 7, vcc
	v_cmp_eq_u32_e32 vcc, 0, v12
	s_and_b64 s[0:1], s[50:51], vcc
	v_cmp_gt_f32_e32 vcc, v10, v11
	s_and_b64 vcc, s[0:1], vcc
	s_nop 0
	v_cndmask_b32_e32 v10, v11, v10, vcc
	v_bitop3_b32 v11, v6, s39, v5 bitop3:0xc8
	v_cndmask_b32_e64 v12, v13, 8, vcc
	v_cmp_eq_u32_e32 vcc, 0, v11
	s_and_b64 s[0:1], s[48:49], vcc
	v_cmp_gt_f32_e32 vcc, v9, v10
	s_and_b64 vcc, s[0:1], vcc
	s_nop 0
	v_cndmask_b32_e32 v9, v10, v9, vcc
	v_bitop3_b32 v10, v6, s69, v5 bitop3:0xc8
	v_cndmask_b32_e64 v11, v12, 9, vcc
	v_cmp_eq_u32_e32 vcc, 0, v10
	s_and_b64 s[0:1], s[46:47], vcc
	v_cmp_gt_f32_e32 vcc, v4, v9
	s_and_b64 vcc, s[0:1], vcc
	s_nop 0
	v_cndmask_b32_e32 v4, v9, v4, vcc
	v_bitop3_b32 v9, v6, s70, v5 bitop3:0xc8
	v_cndmask_b32_e64 v10, v11, 10, vcc
	v_cmp_eq_u32_e32 vcc, 0, v9
	s_and_b64 s[0:1], s[44:45], vcc
	v_cmp_gt_f32_e32 vcc, v3, v4
	s_and_b64 vcc, s[0:1], vcc
	s_nop 0
	v_cndmask_b32_e32 v3, v4, v3, vcc
	v_bitop3_b32 v4, v6, s71, v5 bitop3:0xc8
	v_cndmask_b32_e64 v9, v10, 11, vcc
	v_cmp_eq_u32_e32 vcc, 0, v4
	s_and_b64 s[0:1], s[36:37], vcc
	v_cmp_gt_f32_e32 vcc, v2, v3
	s_and_b64 vcc, s[0:1], vcc
	s_nop 0
	v_cndmask_b32_e32 v2, v3, v2, vcc
	v_bitop3_b32 v3, v6, s72, v5 bitop3:0xc8
	v_cndmask_b32_e64 v4, v9, 12, vcc
	v_cmp_eq_u32_e32 vcc, 0, v3
	s_and_b64 s[0:1], s[34:35], vcc
	v_cmp_gt_f32_e32 vcc, v1, v2
	s_and_b64 vcc, s[0:1], vcc
	s_nop 0
	v_cndmask_b32_e32 v1, v2, v1, vcc
	v_bitop3_b32 v2, v6, s73, v5 bitop3:0xc8
	v_cndmask_b32_e64 v3, v4, 13, vcc
	v_cmp_eq_u32_e32 vcc, 0, v2
	s_and_b64 s[0:1], s[30:31], vcc
	v_cmp_gt_f32_e32 vcc, v0, v1
	s_and_b64 s[0:1], s[0:1], vcc
	v_cndmask_b32_e64 v0, v3, 14, s[0:1]
	v_lshlrev_b32_e64 v1, v0, 1
	v_cmp_lt_i32_e32 vcc, -1, v0
	s_nop 1
	v_cndmask_b32_e32 v0, 0, v1, vcc
	v_or_b32_e32 v2, v0, v7
	v_lshlrev_b64 v[0:1], v23, -1
	v_not_b32_e32 v1, v1
	v_not_b32_e32 v0, v0
	v_mov_b32_e32 v200, 0
.Llist_p1_l0:
	v_lshrrev_b32_e32 v3, s20, v2
	v_and_b32_e32 v3, 1, v3
	v_cmp_eq_u32_e32 vcc, 1, v3
	s_and_b64 s[0:1], vcc, s[2:3]
	v_cndmask_b32_e64 v3, 0, 1, s[0:1]
	v_cmp_ne_u32_e32 vcc, 0, v3
	s_nop 1
	s_bcnt1_i32_b64 s82, vcc
	v_cmp_eq_u32_e64 s[80:81], s20, v22
	v_mov_b32_e32 v203, s82
	s_add_i32 s20, s20, 1
	s_cmp_lg_u32 s76, s20
	v_cndmask_b32_e64 v200, v200, v203, s[80:81]
	s_cbranch_scc1 .Llist_p1_l0
	v_cmp_ne_u32_e32 vcc, 0, v200
	v_lshlrev_b32_e32 v202, 2, v22
	s_and_saveexec_b64 s[80:81], vcc
	s_cbranch_execz .Llist_noat_l0
	global_atomic_add v201, v202, v200, s[26:27] sc0
.Llist_noat_l0:
	s_or_b64 exec, exec, s[80:81]
	s_mov_b32 s20, 0
	s_waitcnt vmcnt(0)
.Llist_p2_l0:
	v_lshrrev_b32_e32 v3, s20, v2
	v_and_b32_e32 v3, 1, v3
	v_cmp_eq_u32_e32 vcc, 1, v3
	s_and_b64 s[0:1], vcc, s[2:3]
	v_cndmask_b32_e64 v3, 0, 1, s[0:1]
	v_cmp_ne_u32_e32 vcc, 0, v3
	s_cbranch_vccz .Llist_nx_l0
	v_readlane_b32 s18, v201, s20
	s_and_saveexec_b64 s[6:7], s[0:1]
	s_cbranch_execz .Llist_rs_l0
	v_and_b32_e32 v4, vcc_lo, v0
	v_and_b32_e32 v3, vcc_hi, v1
	v_bcnt_u32_b32 v4, v4, 0
	v_bcnt_u32_b32 v3, v3, v4
	v_add_u32_e32 v16, s18, v3
	v_cmp_gt_u32_e32 vcc, s71, v16
	s_and_b64 exec, exec, vcc
	s_cbranch_execz .Llist_rs_l0
	v_bfe_u32 v3, v2, 0, s20
	v_bcnt_u32_b32 v3, v3, 0
	v_lshl_or_b32 v3, v3, 12, v21
	v_lshl_add_u64 v[4:5], v[16:17], 2, s[28:29]
	global_store_dword v[4:5], v3, off

; __device__ __forceinline__ void moba_list_item(const Ptrs& P, int bh, int j) {
;     ...
;     for (int n = 0; n < j; ++n) {
;         const bool sb = (((sel >> n) & 1u) != 0u) && (hi == 0);
;         const unsigned long long mk = __ballot(sb);
;         if (mk != 0ull) {
;             unsigned base = 0u;
;             if (lane == 0) base = atomicAdd(P.SELCNT() + bh * 16 + n, (unsigned)__popcll(mk));
;             base = (unsigned)__builtin_amdgcn_readfirstlane((int)base);
;             if (sb) { const unsigned pos = base + (unsigned)__popcll(mk & ((1ull << lane) - 1ull)); const unsigned k = (unsigned)__popc(sel & ((1u << n) - 1u));
;                 if (pos < 4096u) P.LIST()[(size_t)(bh * 16 + n) * 4096 + pos] = (unsigned)t | (k << 12); }
;         }
;     }
.Llist_nx_l0:
	s_add_i32 s20, s20, 1
	s_add_u32 s28, s28, 0x4000
	s_addc_u32 s29, s29, 0
	s_cmp_lg_u32 s76, s20
	s_cbranch_scc1 .Llist_p2_l0
	s_branch .LBB0_757
